# attention key loop: static s_setprio 1 for waves 4-7 (break lockstep of SIMD wave pairs)
# baseline (speedup 1.0000x reference)
; DI float bf_lo(unsigned u) { return __uint_as_float(u << 16); }
; DI float bf_hi(unsigned u) { return __uint_as_float(u & 0xffff0000u); }
; #define GLDS(gp, lp) __builtin_amdgcn_global_load_lds((const unsigned*)(gp), (__attribute__((address_space(3))) unsigned*)(lp), 16, 0, 0)
; #define SB_ __builtin_amdgcn_sched_barrier(0)
; #define ATT64_STORE(base) do { \
;     { uint2* d = (uint2*)((base) + vlo0); d[0] = make_uint2(rv0.x, rv0.y); d[1] = make_uint2(rv0.z, rv0.w); } } while (0)
; DI void attn_item64(const Params& p, int it, char* smem) {
;     ...
;   f32x16 oa[2], ob[2]; oa[0] = zero16(); oa[1] = zero16(); ob[0] = zero16(); ob[1] = zero16();
;   float gk = 0.f;
;   for (int f = 0; f < QKD; ++f) gk = fmaxf(gk, fabsf(p.k_norm_g[f]));
;   float qsa = 0.f, qsb = 0.f;
; #pragma unroll
;   for (int c = 0; c < 6; ++c) {
;     const uint4 u = __builtin_bit_cast(uint4, qfa[c]), v = __builtin_bit_cast(uint4, qfb[c]);
;     qsa += bf_lo(u.x) * bf_lo(u.x) + bf_hi(u.x) * bf_hi(u.x) + bf_lo(u.y) * bf_lo(u.y) + bf_hi(u.y) * bf_hi(u.y) + bf_lo(u.z) * bf_lo(u.z) + bf_hi(u.z) * bf_hi(u.z) + bf_lo(u.w) * bf_lo(u.w) + bf_hi(u.w) * bf_hi(u.w);
;     qsb += bf_lo(v.x) * bf_lo(v.x) + bf_hi(v.x) * bf_hi(v.x) + bf_lo(v.y) * bf_lo(v.y) + bf_hi(v.y) * bf_hi(v.y) + bf_lo(v.z) * bf_lo(v.z) + bf_hi(v.z) * bf_hi(v.z) + bf_lo(v.w) * bf_lo(v.w) + bf_hi(v.w) * bf_hi(v.w);
;   }
;   qsa += __shfl_xor(qsa, 32); qsb += __shfl_xor(qsb, 32);
;   const float negC = -(sqrtf(fmaxf(qsa, qsb)) * gk * 9.797959f * 1.01f);
;   f32x16 sinit;
; #pragma unroll
;   for (int i = 0; i < 16; ++i) sinit[i] = negC;
;   float la = 0.f, lb = 0.f;
;   const int kid0 = t, kid1 = (t & 255) + 512;
;   const bool k1v = t < 256;
;   const int kgo0 = (kid0 / 12) * QKD + (((kid0 % 12) ^ (((kid0 / 12) >> 2) & 3))) * 8, kgo1 = (kid1 / 12) * QKD + (((kid1 % 12) ^ (((kid1 / 12) >> 2) & 3))) * 8;
;   const int klo0 = kid0 * 16, klo1 = kid1 * 16;
;   const int vgo0 = (t >> 3) * NKEY + (t & 7) * 8;
;   const int vlo0 = KBYTES + (t >> 3) * VROW + (t & 7) * 16;
;   uint4 rv0;
;   GLDS(Kb + kgo0, smem + klo0); if (k1v) GLDS(Kb + kgo1, smem + klo1);
;   rv0 = *(const uint4*)(Vb + vgo0);
;   SB_;
;     ...
;   ATT64_STORE(smem);
;   __syncthreads();
.LBB0_547:
	s_or_b64 exec, exec, s[4:5]
	v_ashrrev_i32_e32 v11, 3, v7
	s_movk_i32 s6, 0x900
	v_mul_lo_u32 v12, v11, s6
	v_and_b32_e32 v18, 7, v7
	s_mul_i32 s4, s42, 0x48000
	v_lshl_or_b32 v12, v18, 3, v12
	s_mul_hi_u32 s5, s42, 0x48000
	s_add_u32 s4, s20, s4
	v_ashrrev_i32_e32 v13, 31, v12
	s_addc_u32 s5, s21, s5
	v_lshlrev_b64 v[16:17], 1, v[12:13]
	v_lshl_add_u64 v[12:13], s[4:5], 0, v[16:17]
	global_load_dwordx4 v[12:15], v[12:13], off
	s_waitcnt lgkmcnt(0)
	v_add_f32_e32 v0, v0, v5
	v_add_f32_e32 v1, v1, v10
	v_max_f32_e32 v0, v0, v1
	s_mov_b32 s4, 0xf800000
	v_mul_f32_e32 v1, 0x4f800000, v0
	v_cmp_gt_f32_e64 s[4:5], s4, v0
	s_mov_b32 s8, 1
	s_nop 0
	v_cndmask_b32_e64 v1, v0, v1, s[4:5]
	v_sqrt_f32_e32 v5, v1
	v_mov_b32_e32 v0, 0
	v_add_u32_e32 v10, -1, v5
	v_fma_f32 v19, -v10, v5, v1
	v_cmp_ge_f32_e64 s[6:7], 0, v19
	v_add_u32_e32 v19, 1, v5
	s_nop 0
	v_cndmask_b32_e64 v10, v5, v10, s[6:7]
	v_fma_f32 v5, -v19, v5, v1
	v_cmp_lt_f32_e64 s[6:7], 0, v5
	s_nop 1
	v_cndmask_b32_e64 v5, v10, v19, s[6:7]
	v_mul_f32_e32 v10, 0x37800000, v5
	v_cndmask_b32_e64 v5, v5, v10, s[4:5]
	v_cmp_class_f32_e64 s[4:5], v1, v200
	s_nop 1
	v_cndmask_b32_e64 v1, v5, v1, s[4:5]
	v_mul_f32_e32 v1, v9, v1
	v_mul_f32_e32 v1, 0x411cc471, v1
	s_movk_i32 s4, 0x88
	v_mul_f32_e32 v64, 0xbf8147ae, v1
	v_mul_lo_u32 v1, v11, s4
	v_lshl_add_u32 v209, v18, 4, v1
	v_mov_b32_e32 v65, v64
	v_mov_b32_e32 v66, v64
	v_mov_b32_e32 v67, v64
	v_mov_b32_e32 v68, v64
	v_mov_b32_e32 v69, v64
	v_mov_b32_e32 v70, v64
	v_mov_b32_e32 v71, v64
	v_mov_b32_e32 v72, v64
	v_mov_b32_e32 v73, v64
	v_mov_b32_e32 v74, v64
	v_mov_b32_e32 v75, v64
	v_mov_b32_e32 v76, v64
	v_mov_b32_e32 v77, v64
	v_mov_b32_e32 v78, v64
	v_mov_b32_e32 v79, v64
	s_lshr_b32 s4, s63, 2
	v_add_u32_e32 v1, 0x3000, v209
	s_mul_hi_u32 s5, s4, 0x48000
	s_mul_i32 s6, s4, 0x48000
	s_mul_hi_u32 s7, s4, 0x6c000
	s_mul_i32 s9, s4, 0x6c000
	s_add_u32 s4, s60, s6
	s_waitcnt vmcnt(0)
	ds_write2_b64 v1, v[12:13], v[14:15] offset1:1
	v_lshrrev_b32_e32 v1, 2, v7
	s_addc_u32 s5, s61, s5
	v_lshlrev_b32_e32 v5, 2, v7
	v_xor_b32_e32 v1, v8, v1
	v_lshl_add_u64 v[170:171], s[4:5], 0, v[16:17]
	s_add_u32 s4, s64, s9
	v_and_b32_e32 v210, 32, v5
	v_lshlrev_b32_e32 v1, 4, v1
	s_addc_u32 s5, s65, s7
	v_lshlrev_b32_e32 v168, 1, v4
	v_and_b32_e32 v211, 16, v1
	v_mul_i32_i24_e32 v206, -2, v210
	v_mul_u32_u24_e32 v212, 0xc0, v6
	v_mul_u32_u24_e32 v208, 0x88, v6
	v_mad_u32_u24 v207, v6, s58, v205
	v_lshl_add_u64 v[172:173], v[2:3], 1, s[4:5]
	v_lshl_add_u64 v[174:175], s[4:5], 0, v[168:169]
	v_mov_b32_e32 v1, v0
	v_mov_b32_e32 v2, v0
	v_mov_b32_e32 v3, v0
	v_mov_b32_e32 v4, v0
	v_mov_b32_e32 v5, v0
	v_mov_b32_e32 v6, v0
	v_mov_b32_e32 v7, v0
	v_mov_b32_e32 v8, v0
	v_mov_b32_e32 v9, v0
	v_mov_b32_e32 v10, v0
	v_mov_b32_e32 v11, v0
	v_mov_b32_e32 v12, v0
	v_mov_b32_e32 v13, v0
	v_mov_b32_e32 v14, v0
	v_mov_b32_e32 v15, v0
	v_mov_b32_e32 v32, v0
	v_mov_b32_e32 v33, v0
	v_mov_b32_e32 v34, v0
	v_mov_b32_e32 v35, v0
	v_mov_b32_e32 v36, v0
	v_mov_b32_e32 v37, v0
	v_mov_b32_e32 v38, v0
	v_mov_b32_e32 v39, v0
	v_mov_b32_e32 v40, v0
	v_mov_b32_e32 v41, v0
	v_mov_b32_e32 v42, v0
	v_mov_b32_e32 v43, v0
	v_mov_b32_e32 v44, v0
	v_mov_b32_e32 v45, v0
	v_mov_b32_e32 v46, v0
	v_mov_b32_e32 v47, v0
	v_mov_b32_e32 v48, v0
	v_mov_b32_e32 v49, v0
	v_mov_b32_e32 v50, v0
	v_mov_b32_e32 v51, v0
	v_mov_b32_e32 v52, v0
	v_mov_b32_e32 v53, v0
	v_mov_b32_e32 v54, v0
	v_mov_b32_e32 v55, v0
	v_mov_b32_e32 v56, v0
	v_mov_b32_e32 v57, v0
	v_mov_b32_e32 v58, v0
	v_mov_b32_e32 v59, v0
	v_mov_b32_e32 v60, v0
	v_mov_b32_e32 v61, v0
	v_mov_b32_e32 v62, v0
	v_mov_b32_e32 v63, v0
	v_mov_b32_e32 v16, v0
	v_mov_b32_e32 v17, v0
	v_mov_b32_e32 v18, v0
	v_mov_b32_e32 v19, v0
	v_mov_b32_e32 v20, v0
	v_mov_b32_e32 v21, v0
	v_mov_b32_e32 v22, v0
	v_mov_b32_e32 v23, v0
	v_mov_b32_e32 v24, v0
	v_mov_b32_e32 v25, v0
	v_mov_b32_e32 v26, v0
	v_mov_b32_e32 v27, v0
	v_mov_b32_e32 v28, v0
	v_mov_b32_e32 v29, v0
	v_mov_b32_e32 v30, v0
	v_mov_b32_e32 v31, v0
	v_mov_b32_e32 v166, v0
	v_mov_b32_e32 v167, v0
	v_readfirstlane_b32 s99, v220
	s_cmp_lt_u32 s99, 0x100
	s_cbranch_scc1 .Lattn_prio_skip
	s_setprio 1
.Lattn_prio_skip:
	s_waitcnt lgkmcnt(0)
	s_barrier
	s_branch .LBB0_549

; #define MFMA(a, b, c) __builtin_amdgcn_mfma_f32_32x32x16_bf16((a), (b), (c), 0, 0, 0)
; DI unsigned pk_bf16(float lo, float hi) { f32x2v v = {lo, hi}; bf16x2v b = __builtin_convertvector(v, bf16x2v); return __builtin_bit_cast(unsigned, b); }
; #define SB_ __builtin_amdgcn_sched_barrier(0)
; DI void attn_item64(const Params& p, int it, char* smem) {
;     ...
; #pragma unroll
;     for (int t2 = 0; t2 < 2; ++t2) {
;       const char* kpe = cur + (t2 * 32 + r) * KROW + swo;
;       const char* kpo = kpe - 2 * sb32;
;       f32x16 sa, sb;
;       { const bf16x8 kf = *(const bf16x8*)(kpe); sa = MFMA(kf, qfa[0], sinit); sb = MFMA(kf, qfb[0], sinit); }
; #pragma unroll
;       for (int c = 1; c < 6; ++c) { const bf16x8 kf = *(const bf16x8*)(((c & 1) ? kpo : kpe) + c * 32); sa = MFMA(kf, qfa[c], sa); sb = MFMA(kf, qfb[c], sb); }
;       SB_;
;       float lsa = 0.f, lsb = 0.f;
; #pragma unroll
;       for (int i = 0; i < 16; ++i) { const float e = __builtin_amdgcn_exp2f(sa[i]); sa[i] = e; lsa += e; const float f = __builtin_amdgcn_exp2f(sb[i]); sb[i] = f; lsb += f; }
;       la += lsa; lb += lsb;
;       SB_;
; #pragma unroll
;       for (int s2 = 0; s2 < 2; ++s2) {
;         uint4 pu, pv;
;         pu.x = pk_bf16(sa[8 * s2 + 0], sa[8 * s2 + 1]); pu.y = pk_bf16(sa[8 * s2 + 2], sa[8 * s2 + 3]); pu.z = pk_bf16(sa[8 * s2 + 4], sa[8 * s2 + 5]); pu.w = pk_bf16(sa[8 * s2 + 6], sa[8 * s2 + 7]);
;         pv.x = pk_bf16(sb[8 * s2 + 0], sb[8 * s2 + 1]); pv.y = pk_bf16(sb[8 * s2 + 2], sb[8 * s2 + 3]); pv.z = pk_bf16(sb[8 * s2 + 4], sb[8 * s2 + 5]); pv.w = pk_bf16(sb[8 * s2 + 6], sb[8 * s2 + 7]);
;         const bf16x8 pa_ = __builtin_bit_cast(bf16x8, pu), pb_ = __builtin_bit_cast(bf16x8, pv);
; #pragma unroll
;         for (int vt = 0; vt < 2; ++vt) {
;           const char* vp = cur + KBYTES + (vt * 32 + r) * VROW + (t2 * 32 + 16 * s2 + 4 * hh) * 2;
;           const uint2 lo = *(const uint2*)(vp), hi = *(const uint2*)(vp + 16);
;           uint4 vu; vu.x = lo.x; vu.y = lo.y; vu.z = hi.x; vu.w = hi.y;
;           const bf16x8 vf = __builtin_bit_cast(bf16x8, vu);
;           oa[vt] = MFMA(vf, pa_, oa[vt]);
;           ob[vt] = MFMA(vf, pb_, ob[vt]);
;         }
;       }
.LBB0_551:
	s_setprio 0
	v_add_u32_e32 v168, v211, v210
	v_add_u32_e32 v179, v168, v212
	ds_read_b128 v[160:163], v179 offset:20992
	ds_read_b128 v[170:173], v179 offset:21056
	v_add_u32_e32 v178, v179, v206
	s_waitcnt lgkmcnt(1)
	v_mfma_f32_32x32x16_bf16 v[80:95], v[160:163], v[152:155], v[64:79]
	v_mfma_f32_32x32x16_bf16 v[96:111], v[160:163], v[156:159], v[64:79]
	ds_read_b128 v[160:163], v178 offset:21024
	ds_read_b128 v[174:177], v179 offset:21120
	s_waitcnt lgkmcnt(1)
	v_mfma_f32_32x32x16_bf16 v[80:95], v[160:163], v[136:139], v[80:95]
	v_mfma_f32_32x32x16_bf16 v[96:111], v[160:163], v[140:143], v[96:111]
	v_mfma_f32_32x32x16_bf16 v[80:95], v[170:173], v[144:147], v[80:95]
	v_mfma_f32_32x32x16_bf16 v[96:111], v[170:173], v[148:151], v[96:111]
	ds_read_b128 v[160:163], v178 offset:21088
	ds_read_b128 v[170:173], v178 offset:21152
	s_waitcnt lgkmcnt(1)
	v_mfma_f32_32x32x16_bf16 v[80:95], v[160:163], v[112:115], v[80:95]
	v_mfma_f32_32x32x16_bf16 v[96:111], v[160:163], v[124:127], v[96:111]
	v_mfma_f32_32x32x16_bf16 v[80:95], v[174:177], v[128:131], v[80:95]
	v_mfma_f32_32x32x16_bf16 v[96:111], v[174:177], v[132:135], v[96:111]
	s_waitcnt lgkmcnt(0)
	v_mfma_f32_32x32x16_bf16 v[80:95], v[170:173], v[116:119], v[80:95]
	v_mfma_f32_32x32x16_bf16 v[96:111], v[170:173], v[120:123], v[96:111]
	s_nop 10
	v_exp_f32_e32 v190, v80
	v_exp_f32_e32 v216, v96
	v_exp_f32_e32 v194, v81
	v_exp_f32_e32 v218, v97
	v_exp_f32_e32 v192, v82
	v_exp_f32_e32 v222, v98
	v_exp_f32_e32 v196, v83
	v_exp_f32_e32 v224, v99
	v_exp_f32_e32 v172, v84
	v_exp_f32_e32 v226, v100
	v_exp_f32_e32 v178, v85
	v_exp_f32_e32 v228, v101
	v_exp_f32_e32 v176, v86
	v_exp_f32_e32 v230, v102
	v_exp_f32_e32 v180, v87
	v_exp_f32_e32 v232, v103
	v_exp_f32_e32 v182, v88
	v_exp_f32_e32 v234, v104
	v_exp_f32_e32 v184, v89
	v_exp_f32_e32 v236, v105
	v_exp_f32_e32 v186, v90
	v_exp_f32_e32 v238, v106
	v_exp_f32_e32 v188, v91
	v_exp_f32_e32 v240, v107
	v_exp_f32_e32 v160, v92
	v_exp_f32_e32 v242, v108
	v_exp_f32_e32 v170, v93
	v_exp_f32_e32 v244, v109
	v_exp_f32_e32 v162, v94
	v_exp_f32_e32 v246, v110
	v_exp_f32_e32 v174, v95
	v_exp_f32_e32 v248, v111
	v_add_u32_e32 v80, v164, v208
	v_add_u32_e32 v250, 0x8000, v80
	v_add_u32_e32 v251, 0x9000, v80
	ds_read2_b64 v[108:111], v250 offset0:64 offset1:66
	ds_read2_b64 v[96:99], v250 offset0:68 offset1:70
	ds_read2_b64 v[104:107], v251 offset0:96 offset1:98
	ds_read2_b64 v[100:103], v251 offset0:100 offset1:102
	ds_read_b128 v[208:211], v179 offset:27136
	ds_read_b128 v[212:215], v179 offset:27200
	v_add3_u32 v161, v168, v207, v206
	s_waitcnt lgkmcnt(1)
	v_mfma_f32_32x32x16_bf16 v[80:95], v[208:211], v[152:155], v[64:79]
	v_mfma_f32_32x32x16_bf16 v[64:79], v[208:211], v[156:159], v[64:79]
	ds_read_b128 v[152:155], v161 offset:21024
	ds_read_b128 v[156:159], v179 offset:27264
	s_waitcnt lgkmcnt(1)
	v_mfma_f32_32x32x16_bf16 v[80:95], v[152:155], v[136:139], v[80:95]
	v_mfma_f32_32x32x16_bf16 v[64:79], v[152:155], v[140:143], v[64:79]
	ds_read_b128 v[136:139], v161 offset:21088
	ds_read_b128 v[140:143], v161 offset:21152
	v_mfma_f32_32x32x16_bf16 v[80:95], v[212:215], v[144:147], v[80:95]
	v_mfma_f32_32x32x16_bf16 v[64:79], v[212:215], v[148:151], v[64:79]
	s_waitcnt lgkmcnt(1)
	v_mfma_f32_32x32x16_bf16 v[80:95], v[136:139], v[112:115], v[80:95]
	v_mfma_f32_32x32x16_bf16 v[64:79], v[136:139], v[124:127], v[64:79]
	v_mfma_f32_32x32x16_bf16 v[80:95], v[156:159], v[128:131], v[80:95]
	v_mfma_f32_32x32x16_bf16 v[64:79], v[156:159], v[132:135], v[64:79]
	s_waitcnt lgkmcnt(0)
	v_mfma_f32_32x32x16_bf16 v[80:95], v[140:143], v[116:119], v[80:95]
	v_mfma_f32_32x32x16_bf16 v[64:79], v[140:143], v[120:123], v[64:79]
	s_nop 10
	v_exp_f32_e32 v191, v80
	v_exp_f32_e32 v217, v64
	v_exp_f32_e32 v195, v81
	v_exp_f32_e32 v219, v65
	v_exp_f32_e32 v193, v82
	v_exp_f32_e32 v223, v66
	v_exp_f32_e32 v197, v83
	v_exp_f32_e32 v225, v67
	v_exp_f32_e32 v173, v84
	v_exp_f32_e32 v227, v68
	v_exp_f32_e32 v179, v85
	v_exp_f32_e32 v229, v69
	v_exp_f32_e32 v177, v86
	v_exp_f32_e32 v231, v70
	v_exp_f32_e32 v181, v87
	v_exp_f32_e32 v233, v71
	v_exp_f32_e32 v183, v88
	v_exp_f32_e32 v235, v72
	v_exp_f32_e32 v185, v89
	v_exp_f32_e32 v237, v73
	v_exp_f32_e32 v187, v90
	v_exp_f32_e32 v239, v74
	v_exp_f32_e32 v189, v91
	v_exp_f32_e32 v241, v75
	v_exp_f32_e32 v161, v92
	v_exp_f32_e32 v243, v76
	v_exp_f32_e32 v171, v93
	v_exp_f32_e32 v245, v77
	v_exp_f32_e32 v163, v94
	v_exp_f32_e32 v247, v78
	v_exp_f32_e32 v175, v95
	v_exp_f32_e32 v249, v79
	ds_read2_b64 v[72:75], v250 offset0:72 offset1:74
	ds_read2_b64 v[64:67], v250 offset0:76 offset1:78
	ds_read2_b64 v[76:79], v251 offset0:104 offset1:106
	ds_read2_b64 v[68:71], v251 offset0:108 offset1:110
	v_cvt_pk_bf16_f32 v80, v216, v218
	v_cvt_pk_bf16_f32 v81, v222, v224
	v_cvt_pk_bf16_f32 v82, v226, v228
	v_cvt_pk_bf16_f32 v83, v230, v232
	v_cvt_pk_bf16_f32 v88, v234, v236
	v_cvt_pk_bf16_f32 v89, v238, v240
	v_mfma_f32_32x32x16_bf16 v[32:47], v[108:111], v[80:83], v[32:47]
	v_cvt_pk_bf16_f32 v90, v242, v244
	v_cvt_pk_bf16_f32 v91, v246, v248
	v_add_f32_e64 v86, v216, 0
	v_add_f32_e64 v87, v217, 0
	v_cvt_pk_bf16_f32 v84, v217, v219
	v_pk_add_f32 v[86:87], v[218:219], v[86:87]
	v_cvt_pk_bf16_f32 v85, v223, v225
	v_pk_add_f32 v[86:87], v[222:223], v[86:87]
	v_mfma_f32_32x32x16_bf16 v[0:15], v[104:107], v[80:83], v[0:15]
	v_add_f32_e64 v92, v224, v86
	v_add_f32_e64 v93, v225, v87
	v_cvt_pk_bf16_f32 v86, v227, v229
	v_cvt_pk_bf16_f32 v87, v231, v233
	v_cvt_pk_bf16_f32 v80, v235, v237
	v_cvt_pk_bf16_f32 v81, v239, v241
	v_cvt_pk_bf16_f32 v82, v243, v245
	v_cvt_pk_bf16_f32 v83, v247, v249
	v_mfma_f32_32x32x16_bf16 v[32:47], v[96:99], v[88:91], v[32:47]
	v_add_f32_e64 v92, v226, v92
	v_add_f32_e64 v93, v227, v93
	v_cvt_pk_bf16_f32 v94, v173, v179
	v_add_f32_e64 v92, v228, v92
	v_add_f32_e64 v93, v229, v93
	v_cvt_pk_bf16_f32 v95, v177, v181
	v_pk_add_f32 v[92:93], v[230:231], v[92:93]
	v_cvt_pk_bf16_f32 v112, v183, v185
	v_pk_add_f32 v[92:93], v[232:233], v[92:93]
	v_mfma_f32_32x32x16_bf16 v[0:15], v[100:103], v[88:91], v[0:15]
	v_add_f32_e64 v90, v190, 0
	v_add_f32_e64 v91, v191, 0
	v_add_f32_e64 v92, v234, v92
	v_add_f32_e64 v93, v235, v93
	v_add_f32_e64 v90, v194, v90
	v_add_f32_e64 v91, v195, v91
	v_pk_add_f32 v[92:93], v[236:237], v[92:93]
	v_cvt_pk_bf16_f32 v113, v187, v189
	v_pk_add_f32 v[88:89], v[238:239], v[92:93]
	v_cvt_pk_bf16_f32 v92, v191, v195
	s_waitcnt lgkmcnt(3)
	v_mfma_f32_32x32x16_bf16 v[32:47], v[72:75], v[84:87], v[32:47]
	v_add_f32_e64 v88, v240, v88
	v_add_f32_e64 v89, v241, v89
	v_cvt_pk_bf16_f32 v93, v193, v197
	v_add_f32_e64 v88, v242, v88
	v_add_f32_e64 v89, v243, v89
	s_waitcnt lgkmcnt(0)
	v_pk_add_f32 v[88:89], v[244:245], v[88:89]
	s_barrier
; #define MFMA(a, b, c) __builtin_amdgcn_mfma_f32_32x32x16_bf16((a), (b), (c), 0, 0, 0)
; DI unsigned pk_bf16(float lo, float hi) { f32x2v v = {lo, hi}; bf16x2v b = __builtin_convertvector(v, bf16x2v); return __builtin_bit_cast(unsigned, b); }
; #define SB_ __builtin_amdgcn_sched_barrier(0)
; #define ATT64_STORE(base) do { \
;     { uint2* d = (uint2*)((base) + vlo0); d[0] = make_uint2(rv0.x, rv0.y); d[1] = make_uint2(rv0.z, rv0.w); } } while (0)
; DI void attn_item64(const Params& p, int it, char* smem) {
;     ...
;       for (int s2 = 0; s2 < 2; ++s2) {
;         uint4 pu, pv;
;         pu.x = pk_bf16(sa[8 * s2 + 0], sa[8 * s2 + 1]); pu.y = pk_bf16(sa[8 * s2 + 2], sa[8 * s2 + 3]); pu.z = pk_bf16(sa[8 * s2 + 4], sa[8 * s2 + 5]); pu.w = pk_bf16(sa[8 * s2 + 6], sa[8 * s2 + 7]);
;         pv.x = pk_bf16(sb[8 * s2 + 0], sb[8 * s2 + 1]); pv.y = pk_bf16(sb[8 * s2 + 2], sb[8 * s2 + 3]); pv.z = pk_bf16(sb[8 * s2 + 4], sb[8 * s2 + 5]); pv.w = pk_bf16(sb[8 * s2 + 6], sb[8 * s2 + 7]);
;         const bf16x8 pa_ = __builtin_bit_cast(bf16x8, pu), pb_ = __builtin_bit_cast(bf16x8, pv);
; #pragma unroll
;         for (int vt = 0; vt < 2; ++vt) {
;           const char* vp = cur + KBYTES + (vt * 32 + r) * VROW + (t2 * 32 + 16 * s2 + 4 * hh) * 2;
;           const uint2 lo = *(const uint2*)(vp), hi = *(const uint2*)(vp + 16);
;           uint4 vu; vu.x = lo.x; vu.y = lo.y; vu.z = hi.x; vu.w = hi.y;
;           const bf16x8 vf = __builtin_bit_cast(bf16x8, vu);
;           oa[vt] = MFMA(vf, pa_, oa[vt]);
;           ob[vt] = MFMA(vf, pb_, ob[vt]);
;         }
;       }
;       SB_;
;     }
;     SB_;
;     if (more) { char* nxt = smem + ((kt + 1) & 1) * STAGE; ATT64_STORE(nxt); }
;     __syncthreads();
;   }
;   la += __shfl_xor(la, 32); lb += __shfl_xor(lb, 32);
;   const float inva = 1.f / la, invb = 1.f / lb;
	v_pk_add_f32 v[88:89], v[246:247], v[88:89]
	v_mfma_f32_32x32x16_bf16 v[0:15], v[76:79], v[84:87], v[0:15]
	v_add_f32_e64 v84, v192, v90
	v_add_f32_e64 v85, v193, v91
	v_add_f32_e64 v88, v248, v88
	v_add_f32_e64 v89, v249, v89
	v_add_f32_e64 v114, v196, v84
	v_add_f32_e64 v115, v197, v85
	v_add_f32_e32 v88, v167, v88
	v_pk_add_f32 v[114:115], v[172:173], v[114:115]
	v_add_f32_e32 v116, v88, v89
	v_pk_add_f32 v[114:115], v[178:179], v[114:115]
	v_mfma_f32_32x32x16_bf16 v[32:47], v[64:67], v[80:83], v[32:47]
	v_cvt_pk_bf16_f32 v88, v190, v194
	v_cvt_pk_bf16_f32 v89, v192, v196
	v_cvt_pk_bf16_f32 v90, v172, v178
	v_cvt_pk_bf16_f32 v91, v176, v180
	v_cvt_pk_bf16_f32 v84, v182, v184
	v_cvt_pk_bf16_f32 v85, v186, v188
	v_cvt_pk_bf16_f32 v86, v160, v170
	v_mfma_f32_32x32x16_bf16 v[0:15], v[68:71], v[80:83], v[0:15]
	v_add_f32_e64 v80, v176, v114
	v_add_f32_e64 v81, v177, v115
	v_cvt_pk_bf16_f32 v87, v162, v174
	v_add_f32_e64 v80, v180, v80
	v_add_f32_e64 v81, v181, v81
	v_cvt_pk_bf16_f32 v114, v161, v171
	v_pk_add_f32 v[80:81], v[182:183], v[80:81]
	v_cvt_pk_bf16_f32 v115, v163, v175
	v_pk_add_f32 v[80:81], v[184:185], v[80:81]
	v_mfma_f32_32x32x16_bf16 v[48:63], v[108:111], v[88:91], v[48:63]
	v_add_f32_e64 v80, v186, v80
	v_add_f32_e64 v81, v187, v81
	v_add_f32_e64 v80, v188, v80
	v_add_f32_e64 v81, v189, v81
	v_add_f32_e64 v80, v160, v80
	v_add_f32_e64 v81, v161, v81
	v_pk_add_f32 v[80:81], v[170:171], v[80:81]
	v_mfma_f32_32x32x16_bf16 v[16:31], v[104:107], v[88:91], v[16:31]
	v_add_f32_e64 v80, v162, v80
	v_add_f32_e64 v81, v163, v81
	v_add_f32_e64 v80, v174, v80
	v_add_f32_e64 v81, v175, v81
	v_add_f32_e32 v80, v166, v80
	v_add_f32_e32 v80, v80, v81
	ds_bpermute_b32 v81, v165, v80
	v_mfma_f32_32x32x16_bf16 v[48:63], v[96:99], v[84:87], v[48:63]
	s_waitcnt lgkmcnt(0)
	v_add_f32_e32 v80, v80, v81
	v_div_scale_f32 v82, s[4:5], v80, v80, 1.0
	v_rcp_f32_e32 v83, v82
	ds_bpermute_b32 v81, v165, v116
	v_mfma_f32_32x32x16_bf16 v[16:31], v[100:103], v[84:87], v[16:31]
	v_mov_b32_e32 v165, v169
	v_fma_f32 v88, -v82, v83, 1.0
	v_fmac_f32_e32 v83, v88, v83
	v_div_scale_f32 v88, vcc, 1.0, v80, 1.0
	v_mul_f32_e32 v84, v88, v83
	s_waitcnt lgkmcnt(0)
; DI unsigned pk_bf16(float lo, float hi) { f32x2v v = {lo, hi}; bf16x2v b = __builtin_convertvector(v, bf16x2v); return __builtin_bit_cast(unsigned, b); }
; DI int tid_() { int t = threadIdx.x; asm volatile("" : "+v"(t)); return t; }
; DI void attn_item64(const Params& p, int it, char* smem) {
;     ...
;   la += __shfl_xor(la, 32); lb += __shfl_xor(lb, 32);
;   const float inva = 1.f / la, invb = 1.f / lb;
;   const int b = bh >> 3, hd = bh & 7;
;   const int te_ = tid_();
;   bf16_t* oda = p.attn_o + (size_t)(b * SEQ + qt * 512 + (te_ >> 6) * 64 + (te_ & 31)) * 512 + hd * 64;
;   bf16_t* odb = oda + (size_t)32 * 512;
; #pragma unroll
;   for (int vt = 0; vt < 2; ++vt)
; #pragma unroll
;     for (int q = 0; q < 4; ++q) {
;       uint2 ou; ou.x = pk_bf16(oa[vt][4 * q] * inva, oa[vt][4 * q + 1] * inva); ou.y = pk_bf16(oa[vt][4 * q + 2] * inva, oa[vt][4 * q + 3] * inva);
;       *(uint2*)(oda + vt * 32 + 8 * q + 4 * hh) = ou;
;       uint2 ov; ov.x = pk_bf16(ob[vt][4 * q] * invb, ob[vt][4 * q + 1] * invb); ov.y = pk_bf16(ob[vt][4 * q + 2] * invb, ob[vt][4 * q + 3] * invb);
;       *(uint2*)(odb + vt * 32 + 8 * q + 4 * hh) = ov;
;     }
	v_add_f32_e32 v81, v116, v81
	v_fma_f32 v85, -v82, v84, v88
	v_fmac_f32_e32 v84, v85, v83
	v_div_scale_f32 v85, s[4:5], v81, v81, 1.0
	v_rcp_f32_e32 v86, v85
	v_fma_f32 v82, -v82, v84, v88
	v_mfma_f32_32x32x16_bf16 v[48:63], v[72:75], v[92:95], v[48:63]
	v_div_fmas_f32 v72, v82, v83, v84
	v_fma_f32 v73, -v85, v86, 1.0
	v_fmac_f32_e32 v86, v73, v86
	v_div_scale_f32 v73, vcc, 1.0, v81, 1.0
	v_mul_f32_e32 v74, v73, v86
	v_fma_f32 v75, -v85, v74, v73
	v_mfma_f32_32x32x16_bf16 v[16:31], v[76:79], v[92:95], v[16:31]
	v_fmac_f32_e32 v74, v75, v86
	v_fma_f32 v73, -v85, v74, v73
	v_div_fmas_f32 v73, v73, v86, v74
	s_lshl_b32 s4, s12, 6
	v_div_fixup_f32 v74, v73, v81, 1.0
	v_mov_b32_e32 v73, v220
	s_and_b32 s4, s4, 0xf800
	v_mfma_f32_32x32x16_bf16 v[48:63], v[64:67], v[112:115], v[48:63]
	s_or_b32 s4, s4, s13
	v_and_b32_e32 v64, 0xffffffc0, v73
	v_add_u32_e32 v64, s4, v64
	v_and_or_b32 v64, v73, 31, v64
	v_ashrrev_i32_e32 v65, 31, v64
	v_lshlrev_b64 v[64:65], 10, v[64:65]
	v_mfma_f32_32x32x16_bf16 v[16:31], v[68:71], v[112:115], v[16:31]
	s_lshl_b32 s4, s42, 7
	v_lshl_add_u64 v[64:65], s[22:23], 0, v[64:65]
	s_and_b32 s42, s4, 0x380
	v_lshl_add_u64 v[64:65], v[64:65], 0, s[42:43]
	v_lshl_add_u64 v[64:65], v[64:65], 0, v[164:165]
	v_pk_mul_f32 v[32:33], v[32:33], v[74:75] op_sel_hi:[1,0]
	v_pk_mul_f32 v[34:35], v[34:35], v[74:75] op_sel_hi:[1,0]
	s_mov_b64 s[4:5], 0x8000
	v_cvt_pk_bf16_f32 v32, v32, v33
	v_cvt_pk_bf16_f32 v33, v34, v35
	v_add_co_u32_e32 v34, vcc, s83, v64
	v_pk_mul_f32 v[0:1], v[0:1], v[74:75] op_sel_hi:[1,0]
	v_pk_mul_f32 v[2:3], v[2:3], v[74:75] op_sel_hi:[1,0]
	v_div_fixup_f32 v72, v72, v80, 1.0
	v_lshl_add_u64 v[66:67], v[64:65], 0, s[4:5]
	v_addc_co_u32_e32 v35, vcc, 0, v65, vcc
	v_cvt_pk_bf16_f32 v0, v0, v1
	v_cvt_pk_bf16_f32 v1, v2, v3
	global_store_dwordx2 v[34:35], v[32:33], off
	v_pk_mul_f32 v[32:33], v[52:53], v[72:73] op_sel_hi:[1,0]
	v_pk_mul_f32 v[34:35], v[54:55], v[72:73] op_sel_hi:[1,0]
	global_store_dwordx2 v[66:67], v[0:1], off offset:64
	v_pk_mul_f32 v[0:1], v[20:21], v[72:73] op_sel_hi:[1,0]
	v_pk_mul_f32 v[2:3], v[22:23], v[72:73] op_sel_hi:[1,0]
	v_cvt_pk_bf16_f32 v32, v32, v33
	v_cvt_pk_bf16_f32 v33, v34, v35
	v_cvt_pk_bf16_f32 v0, v0, v1
	v_cvt_pk_bf16_f32 v1, v2, v3
	global_store_dwordx2 v[64:65], v[32:33], off offset:16
	v_pk_mul_f32 v[32:33], v[36:37], v[74:75] op_sel_hi:[1,0]
	v_pk_mul_f32 v[34:35], v[38:39], v[74:75] op_sel_hi:[1,0]
	global_store_dwordx2 v[64:65], v[0:1], off offset:80
	v_pk_mul_f32 v[0:1], v[4:5], v[74:75] op_sel_hi:[1,0]
	v_pk_mul_f32 v[2:3], v[6:7], v[74:75] op_sel_hi:[1,0]
	v_cvt_pk_bf16_f32 v32, v32, v33
	v_cvt_pk_bf16_f32 v33, v34, v35
	v_cvt_pk_bf16_f32 v0, v0, v1
	v_cvt_pk_bf16_f32 v1, v2, v3
	global_store_dwordx2 v[66:67], v[32:33], off offset:16
	v_pk_mul_f32 v[32:33], v[56:57], v[72:73] op_sel_hi:[1,0]
	v_pk_mul_f32 v[34:35], v[58:59], v[72:73] op_sel_hi:[1,0]
	global_store_dwordx2 v[66:67], v[0:1], off offset:80
	v_pk_mul_f32 v[0:1], v[24:25], v[72:73] op_sel_hi:[1,0]
	v_pk_mul_f32 v[2:3], v[26:27], v[72:73] op_sel_hi:[1,0]
	v_cvt_pk_bf16_f32 v32, v32, v33
	v_cvt_pk_bf16_f32 v33, v34, v35
	v_cvt_pk_bf16_f32 v0, v0, v1
	v_cvt_pk_bf16_f32 v1, v2, v3
	global_store_dwordx2 v[64:65], v[32:33], off offset:32
	v_pk_mul_f32 v[32:33], v[40:41], v[74:75] op_sel_hi:[1,0]
	v_pk_mul_f32 v[34:35], v[42:43], v[74:75] op_sel_hi:[1,0]
	global_store_dwordx2 v[64:65], v[0:1], off offset:96
	v_pk_mul_f32 v[0:1], v[8:9], v[74:75] op_sel_hi:[1,0]
	v_pk_mul_f32 v[2:3], v[10:11], v[74:75] op_sel_hi:[1,0]
	v_cvt_pk_bf16_f32 v32, v32, v33
	v_cvt_pk_bf16_f32 v33, v34, v35
	v_cvt_pk_bf16_f32 v0, v0, v1
	v_cvt_pk_bf16_f32 v1, v2, v3
	global_store_dwordx2 v[66:67], v[32:33], off offset:32
	v_pk_mul_f32 v[32:33], v[60:61], v[72:73] op_sel_hi:[1,0]
	v_pk_mul_f32 v[34:35], v[62:63], v[72:73] op_sel_hi:[1,0]
	global_store_dwordx2 v[66:67], v[0:1], off offset:96
	v_pk_mul_f32 v[0:1], v[28:29], v[72:73] op_sel_hi:[1,0]
	v_pk_mul_f32 v[2:3], v[30:31], v[72:73] op_sel_hi:[1,0]
	v_cvt_pk_bf16_f32 v32, v32, v33
	v_cvt_pk_bf16_f32 v33, v34, v35
	v_cvt_pk_bf16_f32 v0, v0, v1
	v_cvt_pk_bf16_f32 v1, v2, v3
	v_pk_mul_f32 v[48:49], v[48:49], v[72:73] op_sel_hi:[1,0]
	v_pk_mul_f32 v[50:51], v[50:51], v[72:73] op_sel_hi:[1,0]
	global_store_dwordx2 v[64:65], v[32:33], off offset:48
	v_pk_mul_f32 v[32:33], v[44:45], v[74:75] op_sel_hi:[1,0]
	v_pk_mul_f32 v[34:35], v[46:47], v[74:75] op_sel_hi:[1,0]
	v_pk_mul_f32 v[16:17], v[16:17], v[72:73] op_sel_hi:[1,0]
	v_pk_mul_f32 v[18:19], v[18:19], v[72:73] op_sel_hi:[1,0]
	global_store_dwordx2 v[64:65], v[0:1], off offset:112
	v_pk_mul_f32 v[0:1], v[12:13], v[74:75] op_sel_hi:[1,0]
	v_pk_mul_f32 v[2:3], v[14:15], v[74:75] op_sel_hi:[1,0]
	v_cvt_pk_bf16_f32 v48, v48, v49
	v_cvt_pk_bf16_f32 v49, v50, v51
	v_cvt_pk_bf16_f32 v32, v32, v33
	v_cvt_pk_bf16_f32 v33, v34, v35
	v_cvt_pk_bf16_f32 v16, v16, v17
	v_cvt_pk_bf16_f32 v17, v18, v19
	v_cvt_pk_bf16_f32 v0, v0, v1
	v_cvt_pk_bf16_f32 v1, v2, v3
	global_store_dwordx2 v[64:65], v[48:49], off
	global_store_dwordx2 v[66:67], v[32:33], off offset:48
	global_store_dwordx2 v[64:65], v[16:17], off offset:64
	global_store_dwordx2 v[66:67], v[0:1], off offset:112
	s_mov_b64 s[4:5], 0

; __global__ void __launch_bounds__(NTH, 2) mega_kernel(Params p) {
;   cg::grid_group grid = cg::this_grid();
;   __shared__ __attribute__((aligned(16))) char smem[SMEM_BYTES];
	.amdhsa_kernel _Z11mega_kernel6Params
		.amdhsa_group_segment_fixed_size 147456
		.amdhsa_private_segment_fixed_size 0
		.amdhsa_kernarg_size 1424
		.amdhsa_user_sgpr_count 2
		.amdhsa_user_sgpr_dispatch_ptr 0
		.amdhsa_user_sgpr_queue_ptr 0
		.amdhsa_user_sgpr_kernarg_segment_ptr 1
		.amdhsa_user_sgpr_dispatch_id 0
		.amdhsa_user_sgpr_kernarg_preload_length 0
		.amdhsa_user_sgpr_kernarg_preload_offset 0
		.amdhsa_user_sgpr_private_segment_size 0
		.amdhsa_uses_dynamic_stack 0
		.amdhsa_enable_private_segment 0
		.amdhsa_system_sgpr_workgroup_id_x 1
		.amdhsa_system_sgpr_workgroup_id_y 0
		.amdhsa_system_sgpr_workgroup_id_z 0
		.amdhsa_system_sgpr_workgroup_info 0
		.amdhsa_system_vgpr_workitem_id 2
		.amdhsa_next_free_vgpr 253
		.amdhsa_next_free_sgpr 100
		.amdhsa_accum_offset 256
		.amdhsa_reserve_vcc 1
		.amdhsa_float_round_mode_32 0
		.amdhsa_float_round_mode_16_64 0
		.amdhsa_float_denorm_mode_32 3
		.amdhsa_float_denorm_mode_16_64 3
		.amdhsa_dx10_clamp 1
		.amdhsa_ieee_mode 1
		.amdhsa_fp16_overflow 0
		.amdhsa_tg_split 0
		.amdhsa_exception_fp_ieee_invalid_op 0
		.amdhsa_exception_fp_denorm_src 0
		.amdhsa_exception_fp_ieee_div_zero 0
		.amdhsa_exception_fp_ieee_overflow 0
		.amdhsa_exception_fp_ieee_underflow 0
		.amdhsa_exception_fp_ieee_inexact 0
		.amdhsa_exception_int_div_zero 0
	.end_amdhsa_kernel

; __global__ void __launch_bounds__(NTH, 2) mega_kernel(Params p) {
;   cg::grid_group grid = cg::this_grid();
;   __shared__ __attribute__((aligned(16))) char smem[SMEM_BYTES];
amdhsa.kernels:
  - .agpr_count:     0
    .args:
      - .offset:         0
        .size:           1168
        .value_kind:     by_value
      - .offset:         1168
        .size:           4
        .value_kind:     hidden_block_count_x
      - .offset:         1172
        .size:           4
        .value_kind:     hidden_block_count_y
      - .offset:         1176
        .size:           4
        .value_kind:     hidden_block_count_z
      - .offset:         1180
        .size:           2
        .value_kind:     hidden_group_size_x
      - .offset:         1182
        .size:           2
        .value_kind:     hidden_group_size_y
      - .offset:         1184
        .size:           2
        .value_kind:     hidden_group_size_z
      - .offset:         1186
        .size:           2
        .value_kind:     hidden_remainder_x
      - .offset:         1188
        .size:           2
        .value_kind:     hidden_remainder_y
      - .offset:         1190
        .size:           2
        .value_kind:     hidden_remainder_z
      - .offset:         1208
        .size:           8
        .value_kind:     hidden_global_offset_x
      - .offset:         1216
        .size:           8
        .value_kind:     hidden_global_offset_y
      - .offset:         1224
        .size:           8
        .value_kind:     hidden_global_offset_z
      - .offset:         1232
        .size:           2
        .value_kind:     hidden_grid_dims
      - .offset:         1256
        .size:           8
        .value_kind:     hidden_multigrid_sync_arg
    .group_segment_fixed_size: 147456
    .kernarg_segment_align: 8
    .kernarg_segment_size: 1424
    .language:       OpenCL C
    .language_version:
      - 2
      - 0
    .max_flat_workgroup_size: 512
    .name:           _Z11mega_kernel6Params
    .private_segment_fixed_size: 0
    .sgpr_count:     106
    .sgpr_spill_count: 4
    .symbol:         _Z11mega_kernel6Params.kd
    .uniform_work_group_size: 1
    .uses_dynamic_stack: false
    .vgpr_count:     253
    .vgpr_spill_count: 0
    .wavefront_size: 64
